# row phases: static s_setprio 1 for waves 4-7
# baseline (speedup 1.0000x reference)
; #define opaque_tid() opaque_tid_w(wid_u)
; template <int MODE> ...
;   const int tid_ = opaque_tid();
;   const int lane = tid_ & 63;
;   const int gw = blockIdx.x * 8 + (tid_ >> 6), GW = gridDim.x * 8;
;   for (int chunk = gw; chunk < NTOK / 16; chunk += GW) {
;     const int row0 = chunk * 16;
;     int s, t, T;
;     row_seq(row0, s, t, T);
;     const float* md = mod + s * 9216;
;     f32x4 Am[4], Bm[4], Gm[4];
; #pragma unroll
;     for (int i = 0; i < 4; ++i) {
;       const int c = i * 256 + lane * 4;
;       if (MODE != 2) {
;         f32x4 np = *(const f32x4*)(npre + c), sc = *(const f32x4*)(md + (shift_idx + 1) * 1024 + c);
;         Am[i] = np * (sc + 1.f);
;         Bm[i] = *(const f32x4*)(md + shift_idx * 1024 + c);
;       }
;       if (MODE != 0) {
;         f32x4 g = *(const f32x4*)(md + gate_idx * 1024 + c), po = *(const f32x4*)(npost + c);
;         Gm[i] = g * po * cgate;
;       }
;     }
.Lgs_138:
	s_or_b64 exec, exec, s[4:5]
	s_mov_b64 s[10:11], s[0:1]
	s_barrier
	s_cmp_ge_u32 s84, 0x100
	s_cbranch_scc0 .Lprio_row_skip_1
	s_setprio 1
.Lprio_row_skip_1:
	s_load_dwordx2 s[2:3], s[10:11], 0x110
	v_mbcnt_lo_u32_b32 v0, -1, 0
	v_mbcnt_hi_u32_b32 v0, -1, v0
	s_lshl_b32 s57, s33, 3
	v_add_u32_e32 v1, s84, v0
	v_ashrrev_i32_e32 v16, 6, v1
	v_add_u32_e32 v62, s57, v16
	s_movk_i32 s4, 0x1800
	s_lshl_b32 s86, s42, 3
	v_cmp_gt_i32_e32 vcc, s4, v62
	s_and_saveexec_b64 s[8:9], vcc
	s_cbranch_execz .LBB0_86
	s_load_dwordx2 s[4:5], s[10:11], 0x30
	v_lshlrev_b32_e32 v0, 2, v0
	v_and_b32_e32 v18, 0xfc, v0
	v_lshlrev_b32_e32 v17, 2, v18
	v_mov_b32_e32 v33, 0
	s_waitcnt lgkmcnt(0)
	global_load_dwordx4 v[0:3], v17, s[4:5]
	global_load_dwordx4 v[4:7], v17, s[4:5] offset:1024
	global_load_dwordx4 v[8:11], v17, s[4:5] offset:2048
	global_load_dwordx4 v[12:15], v17, s[4:5] offset:3072
	s_load_dwordx4 s[4:7], s[10:11], 0x0
	v_lshlrev_b32_e32 v32, 1, v18
	v_lshl_add_u64 v[20:21], s[2:3], 0, v[32:33]
	s_mov_b64 s[12:13], 0x2e90000
	s_add_u32 s10, s2, 0x2800000
	v_lshl_add_u64 v[34:35], v[20:21], 0, s[12:13]
	v_or_b32_e32 v20, 0x100, v18
	v_or_b32_e32 v22, 0x200, v18
	v_or_b32_e32 v24, 0x300, v18
	v_lshlrev_b32_e32 v16, 4, v16
	s_addc_u32 s11, s3, 0
	v_lshl_add_u32 v63, s33, 7, v16
	s_lshl_b32 s18, s42, 7
	s_mov_b64 s[12:13], 0
	s_movk_i32 s19, 0x800
	v_mov_b32_e32 v64, 0xffff8000
	s_mov_b64 s[14:15], 0x1000
	v_lshlrev_b32_e32 v32, 2, v18
	v_lshlrev_b32_e32 v36, 2, v20
	v_mov_b32_e32 v37, v33
	v_lshlrev_b32_e32 v38, 2, v22
	v_mov_b32_e32 v39, v33
	v_lshlrev_b32_e32 v40, 2, v24
	v_mov_b32_e32 v41, v33
	s_movk_i32 s20, 0x7fff
	v_mov_b32_e32 v65, 0x358637bd
	s_mov_b32 s21, 0x800000
	s_movk_i32 s22, 0x17ff
	s_branch .LBB0_80

; #define STG(P, GB) do { const char* _gb = (GB); \
;     _Pragma("unroll") for (int _i = 0; _i < 2; ++_i) { \
;       __builtin_amdgcn_global_load_lds((const unsigned*)(_gb + voff[_i]), \
;         (LAS unsigned*)((LAS char*)(P) + ldsw + _i * 8192), 16, 0, 0); } } while (0)
; __device__ __forceinline__ bool gemm_unit(int i, int nM, int nN, int nwg, int& pm, int& pn) {
;   const long L = (long)i * gridDim.x + blockIdx.x;
;   if (L >= nwg) return false;
;   int wgid = (int)L;
;   { int q = nwg / NXCD, r = nwg % NXCD, xcd = wgid % NXCD, off = wgid / NXCD;
;     wgid = (xcd < r ? xcd * (q + 1) : r * (q + 1) + (xcd - r) * q) + off; }
;   const int nig = WGM * nN, gid = wgid / nig, fm = gid * WGM, gsz = min(nM - fm, WGM);
;   pm = fm + ((wgid % nig) % gsz); pn = (wgid % nig) / gsz;
;   return true;
; __device__ __forceinline__ void gemm_phase(const bf16_t* __restrict__ A, const bf16_t* __restrict__ Bt, bf16_t* __restrict__ C, int M, int N, int K,
;                                            int ldc, const int EPI, char* smem, const int wid_u) {
;     ...
;   const int wid = __builtin_amdgcn_readfirstlane(tid >> 6), lane = tid & 63, wr = wid >> 2, wc = wid & 3, fr = lane & 15, fq = lane >> 4;
;   const int aoff = lds_byte(wr * 64 + fr, fq * 8), boff = lds_byte(wc * 32 + fr, fq * 8);
;   unsigned voff[2];
;   const int ldsw = wid * 1024;
; #pragma unroll
;   for (int _i = 0; _i < 2; ++_i) { int _r, _c; stage_rc(tid * 16 + _i * 8192, _r, _c); voff[_i] = (unsigned)(_r * K + _c) * 2u; }
;   const int nt = K / BK;
;   const size_t kstep = (size_t)BK * 2, hstep = (size_t)HALF * K * 2, tstep = 2 * hstep;
;   int pm, pn, npm = 0, npn = 0, ui = 0;
;   if (!gemm_unit(0, nM, nN, nwg, pm, pn)) return;
;   f32x4 acc[2][2][4][2];
; #pragma unroll
;   for (int a = 0; a < 2; ++a)
; #pragma unroll
;     for (int b = 0; b < 2; ++b)
; #pragma unroll
;       for (int m = 0; m < 4; ++m)
; #pragma unroll
;         for (int n = 0; n < 2; ++n) acc[a][b][m][n] = (f32x4){0.f, 0.f, 0.f, 0.f};
;   bf16x8 At[4][2], B0[2][2], B1[2][2];
;   const char* cA = (const char*)A + (size_t)pm * tstep;
;   const char* cB = (const char*)Bt + (size_t)pn * tstep;
;   STG(SB(0, 0), cB); STG(SA(0, 0), cA); STG(SB(0, 1), cB + hstep); STG(SA(0, 1), cA + hstep);
;   if (wr == 1) BAR;
;   WAIT_V(4); BAR;
;   STG(SB(1, 0), cB + kstep); STG(SA(1, 0), cA + kstep); STG(SB(1, 1), cB + hstep + kstep);
;   WAIT_V(6); BAR;
.LBB0_138:
	s_or_b64 exec, exec, s[4:5]
	s_setprio 0
	s_mov_b64 s[2:3], s[0:1]
	s_waitcnt lgkmcnt(0)
	s_barrier
	s_load_dwordx2 s[4:5], s[2:3], 0x110
	v_mbcnt_lo_u32_b32 v8, -1, 0
	v_mbcnt_hi_u32_b32 v8, -1, v8
	s_cmpk_lt_u32 s33, 0x2100
	v_add_u32_e32 v0, s84, v8
	s_cselect_b64 s[60:61], -1, 0
	v_readfirstlane_b32 s24, v0
	s_cmpk_gt_u32 s33, 0x20ff
	s_mov_b32 s3, 0
	s_cbranch_scc1 .LBB0_150
	v_lshlrev_b32_e32 v1, 4, v0
	v_add_u32_e32 v2, 0x2000, v1
	v_ashrrev_i32_e32 v3, 31, v2
	v_lshrrev_b32_e32 v3, 22, v3
	v_add_u32_e32 v3, v2, v3
	v_ashrrev_i32_e32 v9, 10, v3
	v_mul_i32_i24_e32 v3, 0x400, v9
	v_sub_u32_e32 v2, v2, v3
	v_lshrrev_b32_e32 v3, 4, v2
	v_bitop3_b32 v2, v3, v2, 32 bitop3:0x6c
	v_ashrrev_i32_e32 v3, 31, v2
	v_lshrrev_b32_e32 v3, 26, v3
	v_add_u32_e32 v3, v2, v3
	v_ashrrev_i32_e32 v10, 6, v3
	v_and_b32_e32 v3, 0xc0, v3
	v_sub_u32_e32 v2, v2, v3
	v_mov_b32_e32 v3, 1
	v_ashrrev_i16_sdwa v2, v3, sext(v2) dst_sel:DWORD dst_unused:UNUSED_PAD src0_sel:DWORD src1_sel:BYTE_0
	v_bfe_i32 v12, v2, 0, 16
	v_bfe_i32 v2, v0, 27, 1
	s_waitcnt lgkmcnt(0)
	s_add_u32 s25, s4, 0x2e90000
	v_lshrrev_b32_e32 v2, 22, v2
	s_addc_u32 s26, s5, 0
	v_lshlrev_b32_e32 v4, 3, v9
	v_add_u32_e32 v2, v1, v2
	s_and_b32 s2, s33, 7
	v_and_b32_e32 v4, 0x1ffff0, v4
	v_lshlrev_b32_e32 v5, 5, v9
	v_and_b32_e32 v2, 0xfffffc00, v2
	s_lshr_b32 s7, s33, 3
	s_mulk_i32 s2, 0x420
	v_add_u32_e32 v4, v10, v4
	v_and_b32_e32 v11, 32, v5
	v_sub_u32_e32 v1, v1, v2
	s_add_i32 s2, s2, s7
	v_lshl_or_b32 v4, v4, 10, v11
	v_lshrrev_b32_e32 v2, 4, v1
	s_mul_i32 s7, s2, 0xba2f
	v_add_lshl_u32 v128, v4, v12, 1
	v_bitop3_b32 v1, v2, v1, 32 bitop3:0x6c
	v_ashrrev_i32_e32 v4, 31, v0
	s_lshr_b32 s7, s7, 22
	v_ashrrev_i32_e32 v2, 31, v1
	v_lshrrev_b32_e32 v4, 26, v4
	s_lshl_b32 s9, s7, 2
	s_mulk_i32 s7, 0x58
	v_lshrrev_b32_e32 v2, 26, v2
	v_add_u32_e32 v0, v0, v4
	s_sub_i32 s2, s2, s7
	v_add_u32_e32 v2, v1, v2
	v_ashrrev_i32_e32 v14, 6, v0
	s_and_b32 s7, s2, 3
	s_ashr_i32 s6, s24, 6
	v_ashrrev_i32_e32 v13, 6, v2
	v_lshlrev_b32_e32 v0, 3, v14
	v_and_b32_e32 v2, 0xc0, v2
	s_or_b32 s7, s9, s7
	s_bfe_u32 s2, s2, 0xe0002
	s_ashr_i32 s8, s24, 8
	s_lshl_b32 s27, s6, 10
	v_and_b32_e32 v0, 0x1ffff0, v0
	v_lshlrev_b32_e32 v4, 5, v14
	v_sub_u32_e32 v1, v1, v2
	s_lshl_b32 s9, s7, 19
	s_lshl_b64 s[10:11], s[2:3], 19
	v_add_u32_e32 v0, v13, v0
	v_and_b32_e32 v15, 32, v4
	v_ashrrev_i16_sdwa v1, v3, sext(v1) dst_sel:DWORD dst_unused:UNUSED_PAD src0_sel:DWORD src1_sel:BYTE_0
	s_add_u32 s18, s4, s10
	v_lshl_or_b32 v0, v0, 10, v15
	v_bfe_i32 v16, v1, 0, 16
	s_addc_u32 s19, s5, s11
	s_add_i32 s28, s27, 0
	v_add_lshl_u32 v130, v0, v16, 1
	s_add_i32 m0, s28, 0x10000
	v_mov_b32_e32 v131, 0
	global_load_lds_dwordx4 v130, s[18:19]
	s_add_i32 m0, s28, 0x12000
	s_add_u32 s16, s25, s9
	global_load_lds_dwordx4 v128, s[18:19]
	s_addc_u32 s17, s26, 0
	s_mov_b32 m0, s28
	s_add_i32 s29, s28, 0x2000
	global_load_lds_dwordx4 v130, s[16:17]
	s_mov_b32 m0, s29
	s_add_u32 s10, s18, 0x40000
	global_load_lds_dwordx4 v128, s[16:17]
	s_addc_u32 s11, s19, 0
	s_add_i32 m0, s28, 0x14000
	v_mov_b32_e32 v129, v131
	global_load_lds_dwordx4 v130, s[10:11]
	s_add_i32 m0, s28, 0x16000
	v_lshl_add_u64 v[6:7], s[18:19], 0, v[130:131]
	global_load_lds_dwordx4 v128, s[10:11]
	s_add_u32 s10, s16, 0x40000
	s_addc_u32 s11, s17, 0
	s_add_i32 s30, s28, 0x4000
	s_mov_b32 m0, s30
	s_add_i32 s31, s28, 0x6000
	global_load_lds_dwordx4 v130, s[10:11]
	s_mov_b32 m0, s31
	v_lshl_add_u64 v[4:5], s[18:19], 0, v[128:129]
	global_load_lds_dwordx4 v128, s[10:11]
	v_lshl_add_u64 v[2:3], s[16:17], 0, v[130:131]
	s_cmp_lg_u32 s8, 1
	v_lshl_add_u64 v[0:1], s[16:17], 0, v[128:129]
	s_cbranch_scc1 .LBB0_141
	s_barrier

; #define opaque_tid() opaque_tid_w(wid_u)
; template <int MODE> ...
;   const int tid_ = opaque_tid();
;   const int lane = tid_ & 63;
;   const int gw = blockIdx.x * 8 + (tid_ >> 6), GW = gridDim.x * 8;
;   for (int chunk = gw; chunk < NTOK / 16; chunk += GW) {
;     const int row0 = chunk * 16;
;     int s, t, T;
;     row_seq(row0, s, t, T);
;     const float* md = mod + s * 9216;
;     f32x4 Am[4], Bm[4], Gm[4];
; #pragma unroll
;     for (int i = 0; i < 4; ++i) {
;       const int c = i * 256 + lane * 4;
;       if (MODE != 2) {
;         f32x4 np = *(const f32x4*)(npre + c), sc = *(const f32x4*)(md + (shift_idx + 1) * 1024 + c);
;         Am[i] = np * (sc + 1.f);
;         Bm[i] = *(const f32x4*)(md + shift_idx * 1024 + c);
;       }
;       if (MODE != 0) {
;         f32x4 g = *(const f32x4*)(md + gate_idx * 1024 + c), po = *(const f32x4*)(npost + c);
;         Gm[i] = g * po * cgate;
;       }
;     }
.LBB0_270:
	s_or_b64 exec, exec, s[2:3]
	s_mov_b64 s[12:13], s[0:1]
	s_waitcnt lgkmcnt(0)
	s_barrier
	s_cmp_ge_u32 s84, 0x100
	s_cbranch_scc0 .Lprio_row_skip_4
	s_setprio 1
.Lprio_row_skip_4:
	s_load_dwordx4 s[4:7], s[12:13], 0x108
	v_mbcnt_lo_u32_b32 v0, -1, 0
	v_mbcnt_hi_u32_b32 v0, -1, v0
	s_movk_i32 s2, 0x1800
	v_add_u32_e32 v1, s84, v0
	v_ashrrev_i32_e32 v32, 6, v1
	v_add_u32_e32 v96, s57, v32
	v_cmp_gt_i32_e32 vcc, s2, v96
	s_and_saveexec_b64 s[2:3], vcc
	s_cbranch_execz .LBB0_275
	s_load_dwordx2 s[8:9], s[12:13], 0x58
	s_load_dwordx2 s[10:11], s[12:13], 0x38
	v_lshlrev_b32_e32 v0, 2, v0
	v_and_b32_e32 v34, 0xfc, v0
	v_lshlrev_b32_e32 v33, 2, v34
	v_mov_b32_e32 v49, 0
	s_waitcnt lgkmcnt(0)
	global_load_dwordx4 v[0:3], v33, s[8:9]
	global_load_dwordx4 v[4:7], v33, s[8:9] offset:1024
	global_load_dwordx4 v[8:11], v33, s[10:11]
	global_load_dwordx4 v[12:15], v33, s[10:11] offset:1024
	global_load_dwordx4 v[16:19], v33, s[8:9] offset:2048
	global_load_dwordx4 v[20:23], v33, s[8:9] offset:3072
	global_load_dwordx4 v[24:27], v33, s[10:11] offset:2048
	global_load_dwordx4 v[28:31], v33, s[10:11] offset:3072
	s_load_dwordx4 s[8:11], s[12:13], 0x0
	v_lshlrev_b32_e32 v48, 1, v34
	v_lshl_add_u64 v[36:37], s[6:7], 0, v[48:49]
	s_mov_b64 s[14:15], 0xee90000
	v_lshl_add_u64 v[50:51], v[36:37], 0, s[14:15]
	s_mov_b64 s[14:15], 0x2e90000
	s_add_u32 s12, s6, 0x2800000
	v_lshl_add_u64 v[52:53], v[36:37], 0, s[14:15]
	v_or_b32_e32 v36, 0x100, v34
	v_or_b32_e32 v38, 0x200, v34
	v_or_b32_e32 v40, 0x300, v34
	v_lshlrev_b32_e32 v32, 4, v32
	s_addc_u32 s13, s7, 0
	v_lshl_add_u64 v[54:55], s[4:5], 0, v[48:49]
	v_lshl_add_u32 v97, s33, 7, v32
	s_lshl_b32 s20, s42, 7
	s_mov_b64 s[4:5], 0
	s_movk_i32 s21, 0x800
	v_mov_b32_e32 v98, 0xffff8000
	s_mov_b64 s[14:15], 0x3000
	s_mov_b64 s[16:17], 0x4000
	s_mov_b64 s[18:19], 0x2000
	v_lshlrev_b32_e32 v48, 2, v34
	v_lshlrev_b32_e32 v56, 2, v36
	v_mov_b32_e32 v57, v49
	v_lshlrev_b32_e32 v58, 2, v38
	v_mov_b32_e32 v59, v49
	v_lshlrev_b32_e32 v60, 2, v40
	v_mov_b32_e32 v61, v49
	s_mov_b32 s22, 0x8000
	v_mov_b32_e32 v99, 0x358637bd
	s_mov_b32 s23, 0x800000
	s_movk_i32 s24, 0x17ff

; #define STG(P, GB) do { const char* _gb = (GB); \
;     _Pragma("unroll") for (int _i = 0; _i < 2; ++_i) { \
;       __builtin_amdgcn_global_load_lds((const unsigned*)(_gb + voff[_i]), \
;         (LAS unsigned*)((LAS char*)(P) + ldsw + _i * 8192), 16, 0, 0); } } while (0)
; __device__ __forceinline__ bool gemm_unit(int i, int nM, int nN, int nwg, int& pm, int& pn) {
;   const long L = (long)i * gridDim.x + blockIdx.x;
;   if (L >= nwg) return false;
;   int wgid = (int)L;
;   { int q = nwg / NXCD, r = nwg % NXCD, xcd = wgid % NXCD, off = wgid / NXCD;
;     wgid = (xcd < r ? xcd * (q + 1) : r * (q + 1) + (xcd - r) * q) + off; }
;   const int nig = WGM * nN, gid = wgid / nig, fm = gid * WGM, gsz = min(nM - fm, WGM);
;   pm = fm + ((wgid % nig) % gsz); pn = (wgid % nig) / gsz;
;   return true;
; __device__ __forceinline__ void gemm_phase(const bf16_t* __restrict__ A, const bf16_t* __restrict__ Bt, bf16_t* __restrict__ C, int M, int N, int K,
;                                            int ldc, const int EPI, char* smem, const int wid_u) {
;     ...
;   const int wid = __builtin_amdgcn_readfirstlane(tid >> 6), lane = tid & 63, wr = wid >> 2, wc = wid & 3, fr = lane & 15, fq = lane >> 4;
;   const int aoff = lds_byte(wr * 64 + fr, fq * 8), boff = lds_byte(wc * 32 + fr, fq * 8);
;   unsigned voff[2];
;   const int ldsw = wid * 1024;
; #pragma unroll
;   for (int _i = 0; _i < 2; ++_i) { int _r, _c; stage_rc(tid * 16 + _i * 8192, _r, _c); voff[_i] = (unsigned)(_r * K + _c) * 2u; }
;   const int nt = K / BK;
;   const size_t kstep = (size_t)BK * 2, hstep = (size_t)HALF * K * 2, tstep = 2 * hstep;
;   int pm, pn, npm = 0, npn = 0, ui = 0;
;   if (!gemm_unit(0, nM, nN, nwg, pm, pn)) return;
;   f32x4 acc[2][2][4][2];
; #pragma unroll
;   for (int a = 0; a < 2; ++a)
; #pragma unroll
;     for (int b = 0; b < 2; ++b)
; #pragma unroll
;       for (int m = 0; m < 4; ++m)
; #pragma unroll
;         for (int n = 0; n < 2; ++n) acc[a][b][m][n] = (f32x4){0.f, 0.f, 0.f, 0.f};
;   bf16x8 At[4][2], B0[2][2], B1[2][2];
;   const char* cA = (const char*)A + (size_t)pm * tstep;
;   const char* cB = (const char*)Bt + (size_t)pn * tstep;
;   STG(SB(0, 0), cB); STG(SA(0, 0), cA); STG(SB(0, 1), cB + hstep); STG(SA(0, 1), cA + hstep);
;   if (wr == 1) BAR;
;   WAIT_V(4); BAR;
;   STG(SB(1, 0), cB + kstep); STG(SA(1, 0), cA + kstep); STG(SB(1, 1), cB + hstep + kstep);
;   WAIT_V(6); BAR;
.LBB0_327:
	s_or_b64 exec, exec, s[2:3]
	s_setprio 0
	s_mov_b64 s[2:3], s[0:1]
	s_waitcnt lgkmcnt(0)
	s_barrier
	s_load_dwordx2 s[4:5], s[2:3], 0x110
	v_mbcnt_lo_u32_b32 v8, -1, 0
	v_mbcnt_hi_u32_b32 v8, -1, v8
	s_cmpk_gt_u32 s33, 0xeff
	v_add_u32_e32 v0, s84, v8
	s_nop 0
	v_readfirstlane_b32 s24, v0
	s_cbranch_scc1 .LBB0_339
	v_lshlrev_b32_e32 v1, 4, v0
	v_add_u32_e32 v2, 0x2000, v1
	v_ashrrev_i32_e32 v3, 31, v2
	v_lshrrev_b32_e32 v3, 22, v3
	v_add_u32_e32 v3, v2, v3
	v_ashrrev_i32_e32 v9, 10, v3
	v_mul_i32_i24_e32 v3, 0x400, v9
	v_sub_u32_e32 v2, v2, v3
	v_lshrrev_b32_e32 v3, 4, v2
	v_bitop3_b32 v2, v3, v2, 32 bitop3:0x6c
	v_ashrrev_i32_e32 v3, 31, v2
	v_lshrrev_b32_e32 v3, 26, v3
	v_add_u32_e32 v3, v2, v3
	v_ashrrev_i32_e32 v10, 6, v3
	v_and_b32_e32 v3, 0xc0, v3
	v_sub_u32_e32 v2, v2, v3
	v_mov_b32_e32 v3, 1
	s_waitcnt lgkmcnt(0)
	s_add_u32 s25, s4, 0x2e90000
	v_ashrrev_i16_sdwa v2, v3, sext(v2) dst_sel:DWORD dst_unused:UNUSED_PAD src0_sel:DWORD src1_sel:BYTE_0
	s_addc_u32 s26, s5, 0
	v_bfe_i32 v12, v2, 0, 16
	v_bfe_i32 v2, v0, 27, 1
	s_add_u32 s27, s4, 0x2100000
	v_lshrrev_b32_e32 v2, 22, v2
	s_addc_u32 s28, s5, 0
	v_lshlrev_b32_e32 v4, 3, v9
	v_add_u32_e32 v2, v1, v2
	s_and_b32 s6, s33, 7
	v_and_b32_e32 v4, 0x1ffff0, v4
	v_lshlrev_b32_e32 v5, 5, v9
	v_and_b32_e32 v2, 0xfffffc00, v2
	s_lshr_b32 s7, s33, 3
	s_mulk_i32 s6, 0x1e0
	v_add_u32_e32 v4, v10, v4
	v_and_b32_e32 v11, 32, v5
	v_sub_u32_e32 v1, v1, v2
	s_add_i32 s6, s6, s7
	v_lshl_or_b32 v4, v4, 10, v11
	v_lshrrev_b32_e32 v2, 4, v1
	s_mul_i32 s7, s6, 0xcccd
	v_add_lshl_u32 v128, v4, v12, 1
	v_bitop3_b32 v1, v2, v1, 32 bitop3:0x6c
	v_ashrrev_i32_e32 v4, 31, v0
	s_lshr_b32 s7, s7, 21
	v_ashrrev_i32_e32 v2, 31, v1
	v_lshrrev_b32_e32 v4, 26, v4
	s_lshl_b32 s8, s7, 2
	s_mul_i32 s7, s7, 40
	v_lshrrev_b32_e32 v2, 26, v2
	v_add_u32_e32 v0, v0, v4
	s_sub_i32 s6, s6, s7
	v_add_u32_e32 v2, v1, v2
	v_ashrrev_i32_e32 v14, 6, v0
	s_and_b32 s7, s6, 3
	s_ashr_i32 s3, s24, 6
	v_ashrrev_i32_e32 v13, 6, v2
	v_lshlrev_b32_e32 v0, 3, v14
	v_and_b32_e32 v2, 0xc0, v2
	s_or_b32 s8, s8, s7
	s_bfe_u32 s6, s6, 0xe0002
	s_mov_b32 s7, 0
	s_ashr_i32 s2, s24, 8
	s_lshl_b32 s29, s3, 10
	v_and_b32_e32 v0, 0x1ffff0, v0
	v_lshlrev_b32_e32 v4, 5, v14
	v_sub_u32_e32 v1, v1, v2
	s_lshl_b32 s9, s8, 19
	s_lshl_b64 s[10:11], s[6:7], 19
	v_add_u32_e32 v0, v13, v0
	v_and_b32_e32 v15, 32, v4
	v_ashrrev_i16_sdwa v1, v3, sext(v1) dst_sel:DWORD dst_unused:UNUSED_PAD src0_sel:DWORD src1_sel:BYTE_0
	s_add_u32 s18, s27, s10
	v_lshl_or_b32 v0, v0, 10, v15
	v_bfe_i32 v16, v1, 0, 16
	s_addc_u32 s19, s28, s11
	s_add_i32 s30, s29, 0
	v_add_lshl_u32 v130, v0, v16, 1
	s_add_i32 m0, s30, 0x10000
	v_mov_b32_e32 v131, 0
	global_load_lds_dwordx4 v130, s[18:19]
	s_add_i32 m0, s30, 0x12000
	s_add_u32 s16, s25, s9
	global_load_lds_dwordx4 v128, s[18:19]
	s_addc_u32 s17, s26, 0
	s_mov_b32 m0, s30
	s_add_i32 s31, s30, 0x2000
	global_load_lds_dwordx4 v130, s[16:17]
	s_mov_b32 m0, s31
	s_add_u32 s10, s18, 0x40000
	global_load_lds_dwordx4 v128, s[16:17]
	s_addc_u32 s11, s19, 0
	s_add_i32 m0, s30, 0x14000
	v_mov_b32_e32 v129, v131
	global_load_lds_dwordx4 v130, s[10:11]
	s_add_i32 m0, s30, 0x16000
	v_lshl_add_u64 v[6:7], s[18:19], 0, v[130:131]
	global_load_lds_dwordx4 v128, s[10:11]
	s_add_u32 s10, s16, 0x40000
	s_addc_u32 s11, s17, 0
	s_add_i32 s34, s30, 0x4000
	s_mov_b32 m0, s34
	s_add_i32 s35, s30, 0x6000
	global_load_lds_dwordx4 v130, s[10:11]
	s_mov_b32 m0, s35
	v_lshl_add_u64 v[4:5], s[18:19], 0, v[128:129]
	global_load_lds_dwordx4 v128, s[10:11]
	v_lshl_add_u64 v[2:3], s[16:17], 0, v[130:131]
	s_cmp_lg_u32 s2, 1
	v_lshl_add_u64 v[0:1], s[16:17], 0, v[128:129]
	s_cbranch_scc1 .LBB0_330
	s_barrier

; #define opaque_tid() opaque_tid_w(wid_u)
; template <int MODE> ...
;   const int tid_ = opaque_tid();
;   const int lane = tid_ & 63;
;   const int gw = blockIdx.x * 8 + (tid_ >> 6), GW = gridDim.x * 8;
;   for (int chunk = gw; chunk < NTOK / 16; chunk += GW) {
;     const int row0 = chunk * 16;
;     int s, t, T;
;     row_seq(row0, s, t, T);
;     const float* md = mod + s * 9216;
;     f32x4 Am[4], Bm[4], Gm[4];
; #pragma unroll
;     for (int i = 0; i < 4; ++i) {
;       const int c = i * 256 + lane * 4;
;       if (MODE != 2) {
;         f32x4 np = *(const f32x4*)(npre + c), sc = *(const f32x4*)(md + (shift_idx + 1) * 1024 + c);
;         Am[i] = np * (sc + 1.f);
;         Bm[i] = *(const f32x4*)(md + shift_idx * 1024 + c);
;       }
;       if (MODE != 0) {
;         f32x4 g = *(const f32x4*)(md + gate_idx * 1024 + c), po = *(const f32x4*)(npost + c);
;         Gm[i] = g * po * cgate;
;       }
;     }
.LBB0_962:
	s_or_b64 exec, exec, s[4:5]
	s_mov_b64 s[10:11], s[0:1]
	s_waitcnt lgkmcnt(0)
	s_barrier
	s_cmp_ge_u32 s84, 0x100
	s_cbranch_scc0 .Lprio_row_skip_10
	s_setprio 1
.Lprio_row_skip_10:
	s_load_dwordx4 s[4:7], s[10:11], 0x108
	v_mbcnt_lo_u32_b32 v0, -1, 0
	v_mbcnt_hi_u32_b32 v0, -1, v0
	s_movk_i32 s8, 0x1800
	v_add_u32_e32 v1, s84, v0
	v_ashrrev_i32_e32 v32, 6, v1
	v_add_u32_e32 v96, s57, v32
	v_cmp_gt_i32_e32 vcc, s8, v96
	s_and_saveexec_b64 s[8:9], vcc
	s_cbranch_execz .LBB0_967
	s_load_dwordx2 s[12:13], s[10:11], 0xe0
	s_load_dwordx2 s[14:15], s[10:11], 0x60
	v_lshlrev_b32_e32 v0, 2, v0
	v_and_b32_e32 v34, 0xfc, v0
	v_lshlrev_b32_e32 v33, 2, v34
	v_mov_b32_e32 v49, 0
	s_waitcnt lgkmcnt(0)
	global_load_dwordx4 v[0:3], v33, s[12:13]
	global_load_dwordx4 v[4:7], v33, s[12:13] offset:1024
	global_load_dwordx4 v[8:11], v33, s[14:15]
	global_load_dwordx4 v[12:15], v33, s[14:15] offset:1024
	global_load_dwordx4 v[16:19], v33, s[12:13] offset:2048
	global_load_dwordx4 v[20:23], v33, s[12:13] offset:3072
	global_load_dwordx4 v[24:27], v33, s[14:15] offset:2048
	global_load_dwordx4 v[28:31], v33, s[14:15] offset:3072
	v_lshlrev_b32_e32 v48, 1, v34
	v_lshl_add_u64 v[36:37], s[6:7], 0, v[48:49]
	s_mov_b64 s[12:13], 0xee90000
	v_lshl_add_u64 v[50:51], v[36:37], 0, s[12:13]
	s_mov_b64 s[12:13], 0x2e90000
	s_add_u32 s10, s6, 0x2800000
	v_lshl_add_u64 v[52:53], v[36:37], 0, s[12:13]
	v_or_b32_e32 v36, 0x100, v34
	v_or_b32_e32 v38, 0x200, v34
	v_or_b32_e32 v40, 0x300, v34
	v_lshlrev_b32_e32 v32, 4, v32
	s_addc_u32 s11, s7, 0
	v_lshl_add_u64 v[54:55], s[4:5], 0, v[48:49]
	v_lshl_add_u32 v97, s33, 7, v32
	s_lshl_b32 s18, s42, 7
	s_mov_b64 s[4:5], 0
	s_movk_i32 s19, 0x800
	v_mov_b32_e32 v98, 0xffff8000
	s_mov_b64 s[12:13], 0x6000
	s_mov_b64 s[14:15], 0x7000
	s_mov_b64 s[16:17], 0x5000
	v_lshlrev_b32_e32 v48, 2, v34
	v_lshlrev_b32_e32 v56, 2, v36
	v_lshlrev_b32_e32 v58, 2, v38
	v_mov_b32_e32 v59, v49
	v_lshlrev_b32_e32 v60, 2, v40
	v_mov_b32_e32 v61, v49
	v_mov_b32_e32 v99, 0x358637bd
	s_mov_b32 s20, 0x800000
	s_movk_i32 s21, 0x17ff
	v_mov_b32_e32 v57, v49

; #define STG(P, GB) do { const char* _gb = (GB); \
;     _Pragma("unroll") for (int _i = 0; _i < 2; ++_i) { \
;       __builtin_amdgcn_global_load_lds((const unsigned*)(_gb + voff[_i]), \
;         (LAS unsigned*)((LAS char*)(P) + ldsw + _i * 8192), 16, 0, 0); } } while (0)
; __device__ __forceinline__ bool gemm_unit(int i, int nM, int nN, int nwg, int& pm, int& pn) {
;   const long L = (long)i * gridDim.x + blockIdx.x;
;   if (L >= nwg) return false;
;   int wgid = (int)L;
;   { int q = nwg / NXCD, r = nwg % NXCD, xcd = wgid % NXCD, off = wgid / NXCD;
;     wgid = (xcd < r ? xcd * (q + 1) : r * (q + 1) + (xcd - r) * q) + off; }
;   const int nig = WGM * nN, gid = wgid / nig, fm = gid * WGM, gsz = min(nM - fm, WGM);
;   pm = fm + ((wgid % nig) % gsz); pn = (wgid % nig) / gsz;
;   return true;
; __device__ __forceinline__ void gemm_phase(const bf16_t* __restrict__ A, const bf16_t* __restrict__ Bt, bf16_t* __restrict__ C, int M, int N, int K,
;                                            int ldc, const int EPI, char* smem, const int wid_u) {
;     ...
;   const int wid = __builtin_amdgcn_readfirstlane(tid >> 6), lane = tid & 63, wr = wid >> 2, wc = wid & 3, fr = lane & 15, fq = lane >> 4;
;   const int aoff = lds_byte(wr * 64 + fr, fq * 8), boff = lds_byte(wc * 32 + fr, fq * 8);
;   unsigned voff[2];
;   const int ldsw = wid * 1024;
; #pragma unroll
;   for (int _i = 0; _i < 2; ++_i) { int _r, _c; stage_rc(tid * 16 + _i * 8192, _r, _c); voff[_i] = (unsigned)(_r * K + _c) * 2u; }
;   const int nt = K / BK;
;   const size_t kstep = (size_t)BK * 2, hstep = (size_t)HALF * K * 2, tstep = 2 * hstep;
;   int pm, pn, npm = 0, npn = 0, ui = 0;
;   if (!gemm_unit(0, nM, nN, nwg, pm, pn)) return;
;   f32x4 acc[2][2][4][2];
; #pragma unroll
;   for (int a = 0; a < 2; ++a)
; #pragma unroll
;     for (int b = 0; b < 2; ++b)
; #pragma unroll
;       for (int m = 0; m < 4; ++m)
; #pragma unroll
;         for (int n = 0; n < 2; ++n) acc[a][b][m][n] = (f32x4){0.f, 0.f, 0.f, 0.f};
;   bf16x8 At[4][2], B0[2][2], B1[2][2];
;   const char* cA = (const char*)A + (size_t)pm * tstep;
;   const char* cB = (const char*)Bt + (size_t)pn * tstep;
;   STG(SB(0, 0), cB); STG(SA(0, 0), cA); STG(SB(0, 1), cB + hstep); STG(SA(0, 1), cA + hstep);
;   if (wr == 1) BAR;
;   WAIT_V(4); BAR;
;   STG(SB(1, 0), cB + kstep); STG(SA(1, 0), cA + kstep); STG(SB(1, 1), cB + hstep + kstep);
;   WAIT_V(6); BAR;
.LBB0_1019:
	s_or_b64 exec, exec, s[4:5]
	s_setprio 0
	s_mov_b64 s[4:5], s[0:1]
	s_waitcnt lgkmcnt(0)
	s_barrier
	s_load_dwordx2 s[6:7], s[4:5], 0x110
	v_mbcnt_lo_u32_b32 v8, -1, 0
	v_mbcnt_hi_u32_b32 v8, -1, v8
	s_andn2_b64 vcc, exec, s[60:61]
	v_add_u32_e32 v0, s84, v8
	s_nop 0
	v_readfirstlane_b32 s26, v0
	s_cbranch_vccnz .LBB0_1031
	v_lshlrev_b32_e32 v1, 4, v0
	v_add_u32_e32 v2, 0x2000, v1
	v_ashrrev_i32_e32 v3, 31, v2
	v_lshrrev_b32_e32 v3, 22, v3
	v_add_u32_e32 v3, v2, v3
	v_ashrrev_i32_e32 v9, 10, v3
	v_mul_i32_i24_e32 v3, 0x400, v9
	v_sub_u32_e32 v2, v2, v3
	v_lshrrev_b32_e32 v3, 4, v2
	v_bitop3_b32 v2, v3, v2, 32 bitop3:0x6c
	v_ashrrev_i32_e32 v3, 31, v2
	v_lshrrev_b32_e32 v3, 26, v3
	v_add_u32_e32 v3, v2, v3
	v_ashrrev_i32_e32 v10, 6, v3
	v_and_b32_e32 v3, 0xc0, v3
	v_sub_u32_e32 v2, v2, v3
	v_mov_b32_e32 v3, 1
	s_waitcnt lgkmcnt(0)
	s_add_u32 s27, s6, 0x2e90000
	v_ashrrev_i16_sdwa v2, v3, sext(v2) dst_sel:DWORD dst_unused:UNUSED_PAD src0_sel:DWORD src1_sel:BYTE_0
	s_addc_u32 s28, s7, 0
	v_bfe_i32 v12, v2, 0, 16
	v_bfe_i32 v2, v0, 27, 1
	s_add_u32 s29, s6, 0xb00000
	v_lshrrev_b32_e32 v2, 22, v2
	s_addc_u32 s30, s7, 0
	v_lshlrev_b32_e32 v4, 3, v9
	v_add_u32_e32 v2, v1, v2
	s_and_b32 s8, s33, 7
	v_and_b32_e32 v4, 0x1ffff0, v4
	v_lshlrev_b32_e32 v5, 5, v9
	v_and_b32_e32 v2, 0xfffffc00, v2
	s_lshr_b32 s9, s33, 3
	s_mulk_i32 s8, 0x420
	v_add_u32_e32 v4, v10, v4
	v_and_b32_e32 v11, 32, v5
	v_sub_u32_e32 v1, v1, v2
	s_add_i32 s8, s8, s9
	v_lshl_or_b32 v4, v4, 10, v11
	v_lshrrev_b32_e32 v2, 4, v1
	s_mul_i32 s9, s8, 0xba2f
	v_add_lshl_u32 v128, v4, v12, 1
	v_bitop3_b32 v1, v2, v1, 32 bitop3:0x6c
	v_ashrrev_i32_e32 v4, 31, v0
	s_lshr_b32 s9, s9, 22
	v_ashrrev_i32_e32 v2, 31, v1
	v_lshrrev_b32_e32 v4, 26, v4
	s_lshl_b32 s10, s9, 2
	s_mulk_i32 s9, 0x58
	v_lshrrev_b32_e32 v2, 26, v2
	v_add_u32_e32 v0, v0, v4
	s_sub_i32 s8, s8, s9
	v_add_u32_e32 v2, v1, v2
	v_ashrrev_i32_e32 v14, 6, v0
	s_and_b32 s9, s8, 3
	s_ashr_i32 s5, s26, 6
	v_ashrrev_i32_e32 v13, 6, v2
	v_lshlrev_b32_e32 v0, 3, v14
	v_and_b32_e32 v2, 0xc0, v2
	s_or_b32 s10, s10, s9
	s_bfe_u32 s8, s8, 0xe0002
	s_mov_b32 s9, 0
	s_ashr_i32 s4, s26, 8
	s_lshl_b32 s31, s5, 10
	v_and_b32_e32 v0, 0x1ffff0, v0
	v_lshlrev_b32_e32 v4, 5, v14
	v_sub_u32_e32 v1, v1, v2
	s_lshl_b32 s11, s10, 19
	s_lshl_b64 s[12:13], s[8:9], 19
	v_add_u32_e32 v0, v13, v0
	v_and_b32_e32 v15, 32, v4
	v_ashrrev_i16_sdwa v1, v3, sext(v1) dst_sel:DWORD dst_unused:UNUSED_PAD src0_sel:DWORD src1_sel:BYTE_0
	s_add_u32 s20, s29, s12
	v_lshl_or_b32 v0, v0, 10, v15
	v_bfe_i32 v16, v1, 0, 16
	s_addc_u32 s21, s30, s13
	s_add_i32 s34, s31, 0
	v_add_lshl_u32 v130, v0, v16, 1
	s_add_i32 m0, s34, 0x10000
	v_mov_b32_e32 v131, 0
	global_load_lds_dwordx4 v130, s[20:21]
	s_add_i32 m0, s34, 0x12000
	s_add_u32 s18, s27, s11
	global_load_lds_dwordx4 v128, s[20:21]
	s_addc_u32 s19, s28, 0
	s_mov_b32 m0, s34
	s_add_i32 s35, s34, 0x2000
	global_load_lds_dwordx4 v130, s[18:19]
	s_mov_b32 m0, s35
	s_add_u32 s12, s20, 0x40000
	global_load_lds_dwordx4 v128, s[18:19]
	s_addc_u32 s13, s21, 0
	s_add_i32 m0, s34, 0x14000
	v_mov_b32_e32 v129, v131
	global_load_lds_dwordx4 v130, s[12:13]
	s_add_i32 m0, s34, 0x16000
	v_lshl_add_u64 v[6:7], s[20:21], 0, v[130:131]
	global_load_lds_dwordx4 v128, s[12:13]
	s_add_u32 s12, s18, 0x40000
	s_addc_u32 s13, s19, 0
	s_add_i32 s36, s34, 0x4000
	s_mov_b32 m0, s36
	s_add_i32 s37, s34, 0x6000
	global_load_lds_dwordx4 v130, s[12:13]
	s_mov_b32 m0, s37
	v_lshl_add_u64 v[4:5], s[20:21], 0, v[128:129]
	global_load_lds_dwordx4 v128, s[12:13]
	v_lshl_add_u64 v[2:3], s[18:19], 0, v[130:131]
	s_cmp_lg_u32 s4, 1
	v_lshl_add_u64 v[0:1], s[18:19], 0, v[128:129]
	s_cbranch_scc1 .LBB0_1022
	s_barrier

; #define opaque_tid() opaque_tid_w(wid_u)
; template <int MODE> ...
;   const int tid_ = opaque_tid();
;   const int lane = tid_ & 63;
;   const int gw = blockIdx.x * 8 + (tid_ >> 6), GW = gridDim.x * 8;
;   for (int chunk = gw; chunk < NTOK / 16; chunk += GW) {
;     const int row0 = chunk * 16;
;     int s, t, T;
;     row_seq(row0, s, t, T);
;     const float* md = mod + s * 9216;
;     f32x4 Am[4], Bm[4], Gm[4];
; #pragma unroll
;     for (int i = 0; i < 4; ++i) {
;       const int c = i * 256 + lane * 4;
;       if (MODE != 2) {
;         f32x4 np = *(const f32x4*)(npre + c), sc = *(const f32x4*)(md + (shift_idx + 1) * 1024 + c);
;         Am[i] = np * (sc + 1.f);
;         Bm[i] = *(const f32x4*)(md + shift_idx * 1024 + c);
;       }
;       if (MODE != 0) {
;         f32x4 g = *(const f32x4*)(md + gate_idx * 1024 + c), po = *(const f32x4*)(npost + c);
;         Gm[i] = g * po * cgate;
;       }
;     }
.LBB0_1151:
	s_or_b64 exec, exec, s[2:3]
	s_waitcnt lgkmcnt(0)
	s_barrier
	s_cmp_ge_u32 s84, 0x100
	s_cbranch_scc0 .Lprio_row_skip_13
	s_setprio 1
.Lprio_row_skip_13:
	v_mbcnt_lo_u32_b32 v0, -1, 0
	v_mbcnt_hi_u32_b32 v0, -1, v0
	s_movk_i32 s2, 0x1800
	v_add_u32_e32 v1, s84, v0
	v_ashrrev_i32_e32 v22, 6, v1
	v_add_u32_e32 v46, s57, v22
	v_cmp_gt_i32_e32 vcc, s2, v46
	s_and_saveexec_b64 s[2:3], vcc
	s_cbranch_execz .LBB0_1156
	s_load_dwordx2 s[2:3], s[0:1], 0xe8
	s_load_dwordx4 s[4:7], s[0:1], 0x108
	v_lshlrev_b32_e32 v0, 2, v0
	v_and_b32_e32 v24, 0xfc, v0
	v_lshlrev_b32_e32 v16, 2, v24
	s_waitcnt lgkmcnt(0)
	global_load_dwordx4 v[0:3], v16, s[2:3]
	global_load_dwordx4 v[4:7], v16, s[2:3] offset:1024
	global_load_dwordx4 v[8:11], v16, s[2:3] offset:2048
	global_load_dwordx4 v[12:15], v16, s[2:3] offset:3072
	v_mov_b32_e32 v17, 0
	v_lshlrev_b32_e32 v16, 1, v24
	v_lshl_add_u64 v[18:19], s[6:7], 0, v[16:17]
	s_mov_b64 s[0:1], 0xee90000
	v_or_b32_e32 v26, 0x100, v24
	v_or_b32_e32 v28, 0x200, v24
	v_or_b32_e32 v30, 0x300, v24
	v_lshlrev_b32_e32 v22, 4, v22
	v_lshl_add_u64 v[18:19], v[18:19], 0, s[0:1]
	v_lshl_add_u64 v[20:21], s[4:5], 0, v[16:17]
	v_lshl_add_u32 v47, s33, 7, v22
	s_lshl_b32 s4, s42, 7
	s_mov_b64 s[0:1], 0
	s_movk_i32 s5, 0x800
	v_mov_b32_e32 v48, 0xffff8000
	s_mov_b64 s[2:3], 0x2808000
	v_lshlrev_b32_e32 v22, 2, v24
	v_mov_b32_e32 v23, v17
	v_lshlrev_b32_e32 v24, 2, v26
	v_mov_b32_e32 v25, v17
	v_lshlrev_b32_e32 v26, 2, v28
	v_mov_b32_e32 v27, v17
	v_lshlrev_b32_e32 v28, 2, v30
	v_mov_b32_e32 v29, v17
	v_mov_b32_e32 v49, 0x358637bd
	s_mov_b32 s8, 0x800000
	s_movk_i32 s9, 0x17ff
